# P34 flag-wait and P8 panel-wait acquires issued before their spin loops; P8 epilogue residual-tile loads issued three row groups ahead
# speedup vs baseline: 1.0080x; 1.0026x over previous
; __global__ void __launch_bounds__(512, 2) mega(Args a) {
;     ...
;             const int g = b >> 2;
;             if (tid == 0) { unsigned sp = 0; while (__hip_atomic_load(flg + 64 * g, __ATOMIC_RELAXED, __HIP_MEMORY_SCOPE_AGENT) == 0u) { __builtin_amdgcn_s_sleep(4); if (++sp > (1u << 22)) break; }
;                 __builtin_amdgcn_fence(__ATOMIC_ACQUIRE, "agent"); asm volatile("s_waitcnt vmcnt(0)" ::: "memory"); }
.Lcmb_skip:
.LBB0_793:
	s_or_b64 exec, exec, s[2:3]
	s_mov_b64 s[0:1], exec
	v_readlane_b32 s2, v245, 5
	v_readlane_b32 s3, v245, 6
	s_and_b64 s[2:3], s[0:1], s[2:3]
	s_mov_b64 exec, s[2:3]
	s_cbranch_execz .LBB0_803
	s_lshl_b32 s2, s66, 4
	s_andn2_b32 s2, s2, 63
	s_ashr_i32 s3, s2, 31
	s_lshl_b64 s[2:3], s[2:3], 2
	s_add_u32 s2, s24, s2
	s_addc_u32 s3, s25, s3
	s_mov_b32 s6, 0x400001
	v_mov_b32_e32 v0, 0
	buffer_inv sc1
	s_branch .LBB0_796

; #define LAS __attribute__((address_space(3)))
; #define LBAR() do { asm volatile("s_waitcnt lgkmcnt(0)" ::: "memory"); __builtin_amdgcn_s_barrier(); asm volatile("" ::: "memory"); } while (0)
; __device__ __forceinline__ void s5_out_block2(LAS unsigned char* lds, const bf16* __restrict__ MLAG, const bf16* __restrict__ WC, const bf16* __restrict__ HP, const bf16* __restrict__ U, ...
;     ...
;     const int g = vb >> 2;
;     const int r = lane & 31, h = lane >> 5, rj = r >> 4, rp = r & 15;
;     LBAR();
;     { const u32x4* src = (const u32x4*)(MLAG + (size_t)g * 8192); LAS u32x4* dst = (LAS u32x4*)lds; dst[tid] = src[tid]; dst[tid + 512] = src[tid + 512]; }
; __global__ void __launch_bounds__(512, 2) mega(Args a) {
;     ...
;             if (tid == 0) { unsigned sp = 0; while (__hip_atomic_load(flg + 64 * g, __ATOMIC_RELAXED, __HIP_MEMORY_SCOPE_AGENT) == 0u) { __builtin_amdgcn_s_sleep(4); if (++sp > (1u << 22)) break; }
;                 __builtin_amdgcn_fence(__ATOMIC_ACQUIRE, "agent"); asm volatile("s_waitcnt vmcnt(0)" ::: "memory"); }
;             __syncthreads();
.LBB0_796:
	global_load_dword v1, v0, s[2:3] sc1
	s_mov_b64 s[4:5], -1
	s_waitcnt vmcnt(0)
	v_cmp_ne_u32_e32 vcc, 0, v1
	s_cbranch_vccnz .LBB0_795
	s_sleep 4
	global_load_dword v1, v0, s[2:3] sc1
	s_waitcnt vmcnt(0)
	v_cmp_eq_u32_e32 vcc, 0, v1
	s_cbranch_vccz .LBB0_795
	s_sleep 4
	global_load_dword v1, v0, s[2:3] sc1
	s_waitcnt vmcnt(0)
	v_cmp_eq_u32_e32 vcc, 0, v1
	s_cbranch_vccz .LBB0_795
	s_sleep 4
	global_load_dword v1, v0, s[2:3] sc1
	s_waitcnt vmcnt(0)
	v_cmp_eq_u32_e32 vcc, 0, v1
	s_cbranch_vccz .LBB0_795
	s_sleep 4
	global_load_dword v1, v0, s[2:3] sc1
	s_waitcnt vmcnt(0)
	v_cmp_eq_u32_e32 vcc, 0, v1
	s_cbranch_vccz .LBB0_795
	s_add_i32 s6, s6, -5
	s_cmp_eq_u32 s6, 0
	s_cselect_b64 s[4:5], -1, 0
	s_sleep 4
	s_branch .LBB0_795
.LBB0_802:
	s_waitcnt vmcnt(0)
.LBB0_803:
	s_or_b64 exec, exec, s[0:1]
	s_ashr_i32 s4, s66, 2
	s_ashr_i32 s5, s4, 31
	s_lshl_b64 s[0:1], s[4:5], 14
	v_readlane_b32 s2, v245, 30
	v_readlane_b32 s3, v245, 31
	s_add_u32 s6, s2, s0
	s_addc_u32 s7, s3, s1
	s_waitcnt vmcnt(18)
	v_mov_b32_e32 v153, 0
	v_lshlrev_b32_e32 v152, 4, v186
	v_lshl_add_u64 v[4:5], s[6:7], 0, v[152:153]
	s_movk_i32 s8, 0x2000
	v_add_co_u32_e32 v4, vcc, s8, v4
	s_barrier
	s_waitcnt lgkmcnt(0)
	s_barrier
; #define LAS __attribute__((address_space(3)))
; #define LBAR() do { asm volatile("s_waitcnt lgkmcnt(0)" ::: "memory"); __builtin_amdgcn_s_barrier(); asm volatile("" ::: "memory"); } while (0)
; #define S5O_PREFETCH(ctv) do { const u32x4* us_ = (const u32x4*)(U + ((size_t)g * S + (size_t)(ctv) * 1024) * 16); _Pragma("unroll") for (int i_ = 0; i_ < 4; ++i_) su[i_] = us_[tid + 512 * i_]; \
;         sh = ((const u32x4*)(HP + ((size_t)g * SNC + (ctv) * 32) * 128))[tid]; } while (0)
; __device__ __forceinline__ void s5_out_block2(LAS unsigned char* lds, const bf16* __restrict__ MLAG, const bf16* __restrict__ WC, const bf16* __restrict__ HP, const bf16* __restrict__ U, ...
;     constexpr int UOFF = 16384, UROW = 1040, HOFF = UOFF + 32 * UROW, HROW = 272;
;     const int g = vb >> 2;
;     const int r = lane & 31, h = lane >> 5, rj = r >> 4, rp = r & 15;
;     LBAR();
;     { const u32x4* src = (const u32x4*)(MLAG + (size_t)g * 8192); LAS u32x4* dst = (LAS u32x4*)lds; dst[tid] = src[tid]; dst[tid + 512] = src[tid + 512]; }
;     const LAS unsigned char* ml = lds + rp * 32 + h * 16;
;     const LAS unsigned char* ul = lds + UOFF + r * UROW + h * 16;
;     const LAS unsigned char* hl = lds + HOFF + r * HROW + h * 16;
;     const f32x4 dA = *(const f32x4*)(d_skip + g * 16 + 4 * h), dB = *(const f32x4*)(d_skip + g * 16 + 8 + 4 * h);
;     bf16x8 wc[2][8];
; #pragma unroll
;     for (int q = 0; q < 2; ++q) { const int jj = q ? 15 - wave : wave; const bf16* wcb = WC + ((size_t)g * 512 + jj * 32 + r) * 128 + 8 * h;
; #pragma unroll
;         for (int ks = 0; ks < 8; ++ks) wc[q][ks] = *(const bf16x8*)(wcb + 16 * ks); }
;     u32x4 su[4], sh;
;     ...
;     S5O_PREFETCH(4 * (vb & 3));
	v_addc_co_u32_e32 v5, vcc, 0, v5, vcc
	global_load_dwordx4 v[0:3], v152, s[6:7]
	v_lshrrev_b32_e32 v17, 5, v184
	global_load_dwordx4 v[4:7], v[4:5], off
	s_lshl_b32 s6, s4, 4
	s_ashr_i32 s7, s6, 31
	s_lshl_b64 s[16:17], s[6:7], 2
	s_add_u32 s16, s76, s16
	v_and_b32_e32 v16, 31, v186
	v_lshlrev_b32_e32 v8, 4, v17
	s_addc_u32 s17, s77, s17
	s_lshl_b64 s[4:5], s[4:5], 9
	s_mov_b32 s3, 0
	global_load_dwordx4 v[32:35], v8, s[16:17]
	global_load_dwordx4 v[36:39], v8, s[16:17] offset:32
	v_or_b32_e32 v10, s4, v16
	v_mov_b32_e32 v11, s5
	v_readlane_b32 s16, v245, 32
	s_lshl_b32 s2, s65, 5
	s_sub_i32 s20, 15, s65
	v_mov_b32_e32 v9, v153
	v_readlane_b32 s17, v245, 33
	v_lshl_add_u64 v[14:15], v[10:11], 0, s[2:3]
	s_lshl_b32 s2, s66, 2
	v_lshl_add_u64 v[12:13], s[16:17], 0, v[8:9]
	s_lshl_b32 s16, s20, 5
	s_and_b32 s2, s2, 12
	s_ashr_i32 s17, s16, 31
	s_lshl_b32 s9, s2, 10
	v_lshl_add_u64 v[10:11], v[10:11], 0, s[16:17]
	s_or_b32 s16, s0, s9
	s_mov_b32 s17, s1
	s_lshl_b64 s[16:17], s[16:17], 5
	s_add_u32 s16, s86, s16
	v_lshlrev_b64 v[14:15], 8, v[14:15]
	v_lshlrev_b64 v[10:11], 8, v[10:11]
	s_addc_u32 s17, s87, s17
	v_lshl_add_u64 v[14:15], v[12:13], 0, v[14:15]
	v_lshl_add_u64 v[10:11], v[12:13], 0, v[10:11]
	v_lshl_add_u64 v[12:13], s[16:17], 0, v[152:153]
	v_readlane_b32 s36, v245, 32
	v_readlane_b32 s37, v245, 33
	s_ashr_i32 s38, s66, 2
	s_lshl_b32 s38, s38, 9
	s_lshl_b32 s39, s65, 5
	s_add_i32 s40, s38, s39
	s_sub_i32 s39, 15, s65
	s_lshl_b32 s39, s39, 5
	s_add_i32 s41, s38, s39
	s_lshl_b32 s40, s40, 8
	s_lshl_b32 s41, s41, 8
	v_lshlrev_b32_e32 v223, 4, v184
	v_add_u32_e32 v225, s41, v223
	v_add_u32_e32 v223, s40, v223
	v_add_u32_e32 v224, 0x1000, v223
	v_add_u32_e32 v226, 0x1000, v225
	global_load_dwordx4 v[40:43], v223, s[36:37]
	global_load_dwordx4 v[44:47], v223, s[36:37] offset:1024
	global_load_dwordx4 v[48:51], v223, s[36:37] offset:2048
	global_load_dwordx4 v[52:55], v223, s[36:37] offset:3072
	global_load_dwordx4 v[56:59], v224, s[36:37]
	global_load_dwordx4 v[60:63], v224, s[36:37] offset:1024
	global_load_dwordx4 v[64:67], v224, s[36:37] offset:2048
	global_load_dwordx4 v[68:71], v224, s[36:37] offset:3072
	global_load_dwordx4 v[72:75], v225, s[36:37]
	global_load_dwordx4 v[76:79], v225, s[36:37] offset:1024
	global_load_dwordx4 v[80:83], v225, s[36:37] offset:2048
	global_load_dwordx4 v[84:87], v225, s[36:37] offset:3072
	global_load_dwordx4 v[88:91], v226, s[36:37]
	global_load_dwordx4 v[92:95], v226, s[36:37] offset:1024
	global_load_dwordx4 v[96:99], v226, s[36:37] offset:2048
	v_add_co_u32_e32 v14, vcc, s8, v12
	global_load_dwordx4 v[104:107], v152, s[16:17]
	s_nop 0
	v_addc_co_u32_e32 v15, vcc, 0, v13, vcc
	global_load_dwordx4 v[100:103], v226, s[36:37] offset:3072
	global_load_dwordx4 v[108:111], v[14:15], off
	v_or_b32_e32 v10, 0x400, v186
	s_movk_i32 s9, 0x6000
	v_lshlrev_b32_e32 v11, 4, v10
	v_add_co_u32_e32 v12, vcc, s9, v12
	v_lshl_add_u64 v[154:155], s[14:15], 0, v[152:153]
	s_nop 0
	v_addc_co_u32_e32 v13, vcc, 0, v13, vcc
	global_load_dwordx4 v[112:115], v11, s[16:17]
	global_load_dwordx4 v[116:119], v[12:13], off
	s_lshl_b32 s16, s2, 5
	s_or_b32 s16, s4, s16
	s_mov_b32 s17, s5
	s_lshl_b64 s[16:17], s[16:17], 8
	s_add_u32 s16, s14, s16
	s_addc_u32 s17, s15, s17
	global_load_dwordx4 v[120:123], v152, s[16:17]
	v_add_u32_e32 v11, 0, v152
	s_lshl_b64 s[6:7], s[6:7], 1
	s_movk_i32 s14, 0x110
	s_add_u32 s6, s12, s6
	s_movk_i32 s16, 0x410
	s_addc_u32 s7, s13, s7
	s_waitcnt vmcnt(42)
	v_lshl_add_u64 v[156:157], s[6:7], 0, v[8:9]
	v_readlane_b32 s6, v245, 1
	s_lshl_b32 s18, s20, 1
	v_lshrrev_b32_e32 v9, 6, v10
	v_mul_u32_u24_e32 v9, 0x410, v9
	s_waitcnt vmcnt(41)
	v_bfe_u32 v160, v186, 4, 1
	v_lshlrev_b32_e32 v162, 5, v16
	v_lshlrev_b32_e32 v158, 4, v186
	v_lshlrev_b32_e32 v170, 4, v10
	s_waitcnt vmcnt(24)
	ds_write_b128 v11, v[0:3]
	v_lshlrev_b32_e32 v1, 5, v186
	s_waitcnt vmcnt(23)
	ds_write_b128 v11, v[4:7] offset:8192
	v_lshrrev_b32_e32 v6, 4, v186
	v_mad_u32_u24 v6, v6, s14, 0
	s_lshl_b32 s14, s65, 1
	v_mad_u32_u24 v3, v16, s16, 0
	s_movk_i32 s16, 0xfd00
	s_or_b32 s15, s14, 1
	v_add_u32_e32 v0, 0x200, v186
	v_and_b32_e32 v1, 0x1e0, v1
	v_mad_i32_i24 v4, v16, s16, v3
	v_add_u32_e32 v5, 0x600, v186
	s_and_b32 s16, s6, 0xffffffc0
	s_lshl_b32 s17, s15, 5
	v_mul_u32_u24_e32 v2, 0x410, v16
	v_add3_u32 v161, 0, v1, v8
	v_and_b32_e32 v1, 0x3f0, v152
	v_lshl_add_u32 v163, v17, 3, v3
	v_lshrrev_b32_e32 v3, 6, v186
	v_lshrrev_b32_e32 v0, 6, v0
	v_lshrrev_b32_e32 v5, 6, v5
	s_cmpk_lt_u32 s6, 0x400
	v_add_u32_e32 v1, 0, v1
	v_and_b32_e32 v7, 0xf0, v152
	v_mul_u32_u24_e32 v3, 0x410, v3
	v_mul_u32_u24_e32 v0, 0x410, v0
	v_mul_u32_u24_e32 v5, 0x410, v5
	s_cselect_b64 s[6:7], -1, 0
	s_or_b32 s19, s18, 1
	v_add3_u32 v2, v2, v8, 0
	s_lshl_b32 s20, s20, 6
	s_lshl_b32 s21, s19, 5
	v_add_u32_e32 v164, 0x4000, v2
	s_sub_i32 s22, 29, s14
	v_add_u32_e32 v165, v1, v3
	v_add_u32_e32 v166, v1, v0
	v_add_u32_e32 v167, v1, v9
	v_add_u32_e32 v168, v1, v5
	v_add_u32_e32 v169, v6, v7
	v_add_u32_e32 v171, v4, v8
	s_mul_i32 s38, s65, 0x2200
	s_add_i32 s38, s38, 0xe400
	v_lshrrev_b32_e32 v227, 4, v184
	v_mul_u32_u24_e32 v227, 0x110, v227
	v_and_b32_e32 v187, 15, v184
	v_lshl_add_u32 v227, v187, 4, v227
	v_add_u32_e32 v227, s38, v227
	v_and_b32_e32 v187, 31, v184
	v_mul_u32_u24_e32 v187, 0x110, v187
	v_lshrrev_b32_e32 v222, 5, v184
	v_lshl_add_u32 v187, v222, 4, v187
	v_add_u32_e32 v187, s38, v187
	s_waitcnt vmcnt(0)
	ds_write_b128 v227, v[40:43]
	ds_write_b128 v227, v[44:47] offset:1088
	ds_write_b128 v227, v[48:51] offset:2176
	ds_write_b128 v227, v[52:55] offset:3264
	ds_write_b128 v227, v[56:59] offset:4352
	ds_write_b128 v227, v[60:63] offset:5440
	ds_write_b128 v227, v[64:67] offset:6528
	ds_write_b128 v227, v[68:71] offset:7616
	s_waitcnt lgkmcnt(0)
	ds_read_b128 v[40:43], v187
	ds_read_b128 v[44:47], v187 offset:32
	ds_read_b128 v[48:51], v187 offset:64
	ds_read_b128 v[52:55], v187 offset:96
	ds_read_b128 v[56:59], v187 offset:128
	ds_read_b128 v[60:63], v187 offset:160
	ds_read_b128 v[64:67], v187 offset:192
	ds_read_b128 v[68:71], v187 offset:224
	s_waitcnt lgkmcnt(0)
	ds_write_b128 v227, v[72:75]
	ds_write_b128 v227, v[76:79] offset:1088
	ds_write_b128 v227, v[80:83] offset:2176
	ds_write_b128 v227, v[84:87] offset:3264
	ds_write_b128 v227, v[88:91] offset:4352
	ds_write_b128 v227, v[92:95] offset:5440
	ds_write_b128 v227, v[96:99] offset:6528
	ds_write_b128 v227, v[100:103] offset:7616
	s_waitcnt lgkmcnt(0)
	ds_read_b128 v[72:75], v187
	ds_read_b128 v[76:79], v187 offset:32
	ds_read_b128 v[80:83], v187 offset:64
	ds_read_b128 v[84:87], v187 offset:96
	ds_read_b128 v[88:91], v187 offset:128
	ds_read_b128 v[92:95], v187 offset:160
	ds_read_b128 v[96:99], v187 offset:192
	ds_read_b128 v[100:103], v187 offset:224
	s_waitcnt lgkmcnt(0)
	s_branch .LBB0_805

; #define EDN_LOAD(P, row) do { const float* s_ = H1 + (size_t)(row) * 2048 + col0; P[0][0] = *(const f32x4*)s_; P[0][1] = *(const f32x4*)(s_ + 4); P[1][0] = *(const f32x4*)(s_ + 128); P[1][1] = *(const f32x4*)(s_ + 132); } while (0)
;     __device__ __forceinline__ void operator()(const pg8::f32x4 (&acc)[2][2][4][2], const pg8::Unit& u, int wr, int wc, int fr, int fq) const {
;     ...
;         EDN_LOAD(pa, row0);
; #pragma unroll
;         for (int g = 0; g < 8; ++g) {
;             const int ai = g >> 2, m = g & 3, row = row0 + ai * 128 + m * 16;
;             if (g < 7) { const int row2 = row0 + ((g + 1) >> 2) * 128 + ((g + 1) & 3) * 16; if (g & 1) EDN_LOAD(pa, row2); else EDN_LOAD(pb, row2); }
;             float s = 0.f;
; #pragma unroll
;             for (int bj = 0; bj < 2; ++bj)
; #pragma unroll
;                 for (int n = 0; n < 2; ++n) { const f32x4 hv = h[ai][bj][m][n] + ((g & 1) ? pb[bj][n] : pa[bj][n]); h[ai][bj][m][n] = hv; s += (hv[0] * hv[0] + hv[1] * hv[1]) + (hv[2] * hv[2] + hv[3] * hv[3]); }
;             s += __shfl_xor(s, 16); s += __shfl_xor(s, 32);
;             if (fq == 0) atomicAdd(ss + row, s);
.LBB0_1127:
	v_lshl_add_u32 v164, s49, 8, v185
	v_ashrrev_i32_e32 v165, 31, v164
	v_lshl_or_b32 v144, s50, 8, v187
	v_lshlrev_b64 v[128:129], 12, v[164:165]
	v_lshl_add_u64 v[128:129], s[82:83], 0, v[128:129]
	v_lshlrev_b32_e32 v130, 1, v144
	v_mov_b32_e32 v131, v145
	v_lshl_add_u64 v[128:129], v[128:129], 0, v[130:131]
	global_load_dwordx4 v[154:157], v[128:129], off
	global_load_dwordx4 v[166:169], v[128:129], off offset:256
	v_or_b32_e32 v160, 16, v164
	v_ashrrev_i32_e32 v161, 31, v160
	v_lshlrev_b64 v[128:129], 12, v[160:161]
	v_lshl_add_u64 v[128:129], s[82:83], 0, v[128:129]
	v_lshl_add_u64 v[128:129], v[128:129], 0, v[130:131]
	global_load_dwordx4 v[132:135], v[128:129], off
	s_nop 0
	global_load_dwordx4 v[128:131], v[128:129], off offset:256
	v_lshlrev_b32_e32 v200, 12, v164
	v_lshl_add_u32 v200, v144, 1, v200
	v_add_u32_e32 v244, 0x20000, v200
	global_load_dwordx4 v[202:205], v244, s[82:83]
	global_load_dwordx4 v[206:209], v244, s[82:83] offset:256
	v_add_u32_e32 v244, 0x30000, v200
	global_load_dwordx4 v[210:213], v244, s[82:83]
	global_load_dwordx4 v[214:217], v244, s[82:83] offset:256
	v_add_u32_e32 v244, 0x80000, v200
	global_load_dwordx4 v[218:221], v244, s[82:83]
	global_load_dwordx4 v[222:225], v244, s[82:83] offset:256
	v_and_b32_e32 v159, 64, v191
	v_xor_b32_e32 v158, 16, v191
	v_add_u32_e32 v174, 64, v159
	v_cmp_lt_i32_e32 vcc, v158, v174
	s_waitcnt vmcnt(8)
	v_and_b32_e32 v159, 0xffff0000, v154
	v_cndmask_b32_e32 v158, v191, v158, vcc
	v_lshlrev_b32_e32 v182, 2, v158
	v_lshlrev_b32_e32 v158, 16, v154
	v_lshlrev_b32_e32 v154, 16, v155
	v_and_b32_e32 v155, 0xffff0000, v155
	v_lshlrev_b32_e32 v162, 16, v156
	v_and_b32_e32 v163, 0xffff0000, v156
	v_lshlrev_b32_e32 v156, 16, v157
	v_and_b32_e32 v157, 0xffff0000, v157
	v_lshlrev_b32_e32 v170, 16, v166
	v_and_b32_e32 v171, 0xffff0000, v166
	v_lshlrev_b32_e32 v166, 16, v167
	v_and_b32_e32 v167, 0xffff0000, v167
	v_lshlrev_b32_e32 v172, 16, v168
	v_and_b32_e32 v173, 0xffff0000, v168
	v_lshlrev_b32_e32 v168, 16, v169
	v_and_b32_e32 v169, 0xffff0000, v169
	v_pk_add_f32 v[126:127], v[126:127], v[154:155]
	v_pk_add_f32 v[124:125], v[124:125], v[158:159]
	v_pk_add_f32 v[122:123], v[122:123], v[156:157]
	v_pk_add_f32 v[120:121], v[120:121], v[162:163]
	v_pk_add_f32 v[154:155], v[118:119], v[166:167]
	v_pk_add_f32 v[156:157], v[116:117], v[170:171]
	v_pk_add_f32 v[158:159], v[114:115], v[168:169]
	v_pk_add_f32 v[162:163], v[112:113], v[172:173]
	v_mul_f32_e32 v112, v125, v125
	v_mul_f32_e32 v113, v127, v127
	v_mul_f32_e32 v114, v121, v121
	v_mul_f32_e32 v115, v123, v123
	v_mul_f32_e32 v116, v157, v157
	v_mul_f32_e32 v117, v155, v155
	v_fmac_f32_e32 v112, v124, v124
	v_fmac_f32_e32 v113, v126, v126
	v_fmac_f32_e32 v114, v120, v120
	v_fmac_f32_e32 v115, v122, v122
	v_mul_f32_e32 v118, v163, v163
	v_mul_f32_e32 v119, v159, v159
	v_fmac_f32_e32 v116, v156, v156
	v_fmac_f32_e32 v117, v154, v154
	v_add_f32_e32 v112, v112, v113
	v_add_f32_e32 v113, v114, v115
	v_fmac_f32_e32 v118, v162, v162
	v_fmac_f32_e32 v119, v158, v158
	v_add_f32_e32 v114, v116, v117
	v_add_f32_e32 v112, v112, v113
	v_add_f32_e32 v112, v112, v114
	v_add_f32_e32 v113, v118, v119
	v_add_f32_e32 v112, v113, v112
	ds_bpermute_b32 v113, v182, v112
	v_xor_b32_e32 v114, 32, v191
	v_cmp_lt_i32_e32 vcc, v114, v174
	v_lshl_add_u64 v[170:171], v[164:165], 2, s[16:17]
	s_waitcnt lgkmcnt(0)
	v_add_f32_e32 v112, v112, v113
	v_cndmask_b32_e32 v114, v191, v114, vcc
	v_lshlrev_b32_e32 v183, 2, v114
	ds_bpermute_b32 v113, v183, v112
	s_and_saveexec_b64 s[0:1], s[4:5]
	s_cbranch_execz .LBB0_1129
	s_waitcnt lgkmcnt(0)
	v_add_f32_e32 v112, v112, v113
	v_mov_b32_e32 v236, v112
	v_lshlrev_b32_e32 v228, 2, v164
.LBB0_1129:
	s_or_b64 exec, exec, s[0:1]
	v_or_b32_e32 v166, 32, v164
	v_ashrrev_i32_e32 v167, 31, v166
	s_waitcnt lgkmcnt(0)
	v_lshlrev_b64 v[112:113], 12, v[166:167]
	v_lshl_add_u64 v[112:113], s[82:83], 0, v[112:113]
	v_lshlrev_b32_e32 v180, 1, v144
	v_mov_b32_e32 v181, v145
	v_lshl_add_u64 v[112:113], v[112:113], 0, v[180:181]
	s_waitcnt vmcnt(4)
	v_mov_b32_e32 v116, v202
	v_mov_b32_e32 v117, v203
	v_mov_b32_e32 v118, v204
	v_mov_b32_e32 v119, v205
	v_mov_b32_e32 v112, v206
	v_mov_b32_e32 v113, v207
	v_mov_b32_e32 v114, v208
	v_mov_b32_e32 v115, v209
	v_add_u32_e32 v244, 0x90000, v200
	global_load_dwordx4 v[202:205], v244, s[82:83]
	global_load_dwordx4 v[206:209], v244, s[82:83] offset:256
	s_nop 0
	v_lshlrev_b32_e32 v168, 16, v132
	v_and_b32_e32 v169, 0xffff0000, v132
	v_lshlrev_b32_e32 v132, 16, v133
	v_and_b32_e32 v133, 0xffff0000, v133
	v_pk_add_f32 v[110:111], v[110:111], v[132:133]
	v_pk_add_f32 v[108:109], v[108:109], v[168:169]
	v_lshlrev_b32_e32 v174, 16, v128
	v_and_b32_e32 v175, 0xffff0000, v128
	v_lshlrev_b32_e32 v176, 16, v129
	v_and_b32_e32 v177, 0xffff0000, v129
	v_mul_f32_e32 v128, v109, v109
	v_mul_f32_e32 v129, v111, v111
	v_lshlrev_b32_e32 v172, 16, v134
	v_and_b32_e32 v173, 0xffff0000, v134
	v_lshlrev_b32_e32 v134, 16, v135
	v_and_b32_e32 v135, 0xffff0000, v135
	v_fmac_f32_e32 v128, v108, v108
	v_fmac_f32_e32 v129, v110, v110
	v_lshlrev_b32_e32 v178, 16, v130
	v_and_b32_e32 v179, 0xffff0000, v130
	v_add_f32_e32 v130, v128, v129
	v_pk_add_f32 v[106:107], v[106:107], v[134:135]
	v_pk_add_f32 v[128:129], v[104:105], v[172:173]
	v_mul_f32_e32 v105, v107, v107
	v_mul_f32_e32 v104, v129, v129
	v_fmac_f32_e32 v104, v128, v128
	v_fmac_f32_e32 v105, v106, v106
	v_add_f32_e32 v104, v104, v105
	v_lshlrev_b32_e32 v192, 16, v131
	v_and_b32_e32 v193, 0xffff0000, v131
	v_add_f32_e32 v104, v130, v104
	v_pk_add_f32 v[130:131], v[102:103], v[176:177]
	v_pk_add_f32 v[132:133], v[100:101], v[174:175]
	v_mul_f32_e32 v101, v131, v131
	v_mul_f32_e32 v100, v133, v133
	v_pk_add_f32 v[134:135], v[98:99], v[192:193]
	v_pk_add_f32 v[168:169], v[96:97], v[178:179]
	v_fmac_f32_e32 v100, v132, v132
	v_fmac_f32_e32 v101, v130, v130
	v_mul_f32_e32 v96, v169, v169
	v_mul_f32_e32 v97, v135, v135
	v_add_f32_e32 v100, v100, v101
	v_fmac_f32_e32 v96, v168, v168
	v_fmac_f32_e32 v97, v134, v134
	v_add_f32_e32 v100, v104, v100
	v_add_f32_e32 v96, v96, v97
	v_add_f32_e32 v96, v96, v100
	ds_bpermute_b32 v97, v182, v96
	s_waitcnt lgkmcnt(0)
	v_add_f32_e32 v96, v96, v97
	ds_bpermute_b32 v97, v183, v96
	s_and_saveexec_b64 s[0:1], s[4:5]
	s_cbranch_execz .LBB0_1131
	v_lshl_add_u64 v[98:99], v[160:161], 2, s[16:17]
	s_waitcnt lgkmcnt(0)
	v_add_f32_e32 v96, v96, v97
	v_mov_b32_e32 v237, v96
	v_lshlrev_b32_e32 v229, 2, v160
; #define EDN_LOAD(P, row) do { const float* s_ = H1 + (size_t)(row) * 2048 + col0; P[0][0] = *(const f32x4*)s_; P[0][1] = *(const f32x4*)(s_ + 4); P[1][0] = *(const f32x4*)(s_ + 128); P[1][1] = *(const f32x4*)(s_ + 132); } while (0)
;     __device__ __forceinline__ void operator()(const pg8::f32x4 (&acc)[2][2][4][2], const pg8::Unit& u, int wr, int wc, int fr, int fq) const {
;     ...
;         for (int g = 0; g < 8; ++g) {
;             const int ai = g >> 2, m = g & 3, row = row0 + ai * 128 + m * 16;
;             if (g < 7) { const int row2 = row0 + ((g + 1) >> 2) * 128 + ((g + 1) & 3) * 16; if (g & 1) EDN_LOAD(pa, row2); else EDN_LOAD(pb, row2); }
;             float s = 0.f;
; #pragma unroll
;             for (int bj = 0; bj < 2; ++bj)
; #pragma unroll
;                 for (int n = 0; n < 2; ++n) { const f32x4 hv = h[ai][bj][m][n] + ((g & 1) ? pb[bj][n] : pa[bj][n]); h[ai][bj][m][n] = hv; s += (hv[0] * hv[0] + hv[1] * hv[1]) + (hv[2] * hv[2] + hv[3] * hv[3]); }
;             s += __shfl_xor(s, 16); s += __shfl_xor(s, 32);
;             if (fq == 0) atomicAdd(ss + row, s);
.LBB0_1131:
	s_or_b64 exec, exec, s[0:1]
	v_or_b32_e32 v104, 48, v164
	v_ashrrev_i32_e32 v105, 31, v104
	s_waitcnt lgkmcnt(0)
	v_lshlrev_b64 v[96:97], 12, v[104:105]
	v_lshl_add_u64 v[96:97], s[82:83], 0, v[96:97]
	v_lshl_add_u64 v[96:97], v[96:97], 0, v[180:181]
	s_waitcnt vmcnt(4)
	v_mov_b32_e32 v100, v210
	v_mov_b32_e32 v101, v211
	v_mov_b32_e32 v102, v212
	v_mov_b32_e32 v103, v213
	v_mov_b32_e32 v96, v214
	v_mov_b32_e32 v97, v215
	v_mov_b32_e32 v98, v216
	v_mov_b32_e32 v99, v217
	v_add_u32_e32 v244, 0xa0000, v200
	global_load_dwordx4 v[210:213], v244, s[82:83]
	global_load_dwordx4 v[214:217], v244, s[82:83] offset:256
	s_nop 0
	v_lshlrev_b32_e32 v172, 16, v116
	v_and_b32_e32 v173, 0xffff0000, v116
	v_lshlrev_b32_e32 v116, 16, v117
	v_and_b32_e32 v117, 0xffff0000, v117
	v_lshlrev_b32_e32 v174, 16, v118
	v_and_b32_e32 v175, 0xffff0000, v118
	v_lshlrev_b32_e32 v118, 16, v119
	v_and_b32_e32 v119, 0xffff0000, v119
	v_lshlrev_b32_e32 v176, 16, v112
	v_and_b32_e32 v177, 0xffff0000, v112
	v_lshlrev_b32_e32 v178, 16, v113
	v_and_b32_e32 v179, 0xffff0000, v113
	v_lshlrev_b32_e32 v192, 16, v114
	v_and_b32_e32 v193, 0xffff0000, v114
	v_lshlrev_b32_e32 v194, 16, v115
	v_and_b32_e32 v195, 0xffff0000, v115
	v_pk_add_f32 v[94:95], v[94:95], v[116:117]
	v_pk_add_f32 v[114:115], v[92:93], v[172:173]
	v_pk_add_f32 v[112:113], v[90:91], v[118:119]
	v_pk_add_f32 v[118:119], v[88:89], v[174:175]
	v_mul_f32_e32 v92, v115, v115
	v_mul_f32_e32 v93, v95, v95
	v_mul_f32_e32 v88, v119, v119
	v_mul_f32_e32 v89, v113, v113
	v_fmac_f32_e32 v92, v114, v114
	v_fmac_f32_e32 v93, v94, v94
	v_fmac_f32_e32 v88, v118, v118
	v_fmac_f32_e32 v89, v112, v112
	v_add_f32_e32 v92, v92, v93
	v_add_f32_e32 v88, v88, v89
	v_pk_add_f32 v[116:117], v[86:87], v[178:179]
	v_pk_add_f32 v[172:173], v[84:85], v[176:177]
	v_add_f32_e32 v88, v92, v88
	v_mul_f32_e32 v84, v173, v173
	v_mul_f32_e32 v85, v117, v117
	v_pk_add_f32 v[90:91], v[82:83], v[194:195]
	v_pk_add_f32 v[92:93], v[80:81], v[192:193]
	v_fmac_f32_e32 v84, v172, v172
	v_fmac_f32_e32 v85, v116, v116
	v_mul_f32_e32 v80, v93, v93
	v_mul_f32_e32 v81, v91, v91
	v_add_f32_e32 v84, v84, v85
	v_fmac_f32_e32 v80, v92, v92
	v_fmac_f32_e32 v81, v90, v90
	v_add_f32_e32 v84, v88, v84
	v_add_f32_e32 v80, v80, v81
	v_add_f32_e32 v80, v80, v84
	ds_bpermute_b32 v81, v182, v80
	s_waitcnt lgkmcnt(0)
	v_add_f32_e32 v80, v80, v81
	ds_bpermute_b32 v81, v183, v80
	s_and_saveexec_b64 s[0:1], s[4:5]
	s_cbranch_execz .LBB0_1133
	v_lshl_add_u64 v[82:83], v[166:167], 2, s[16:17]
	s_waitcnt lgkmcnt(0)
	v_add_f32_e32 v80, v80, v81
	v_mov_b32_e32 v238, v80
	v_lshlrev_b32_e32 v230, 2, v166
.LBB0_1133:
	s_or_b64 exec, exec, s[0:1]
	v_add_u32_e32 v88, 0x80, v164
	v_ashrrev_i32_e32 v89, 31, v88
	s_waitcnt lgkmcnt(0)
	v_lshlrev_b64 v[80:81], 12, v[88:89]
	v_lshl_add_u64 v[80:81], s[82:83], 0, v[80:81]
	v_mov_b32_e32 v181, v145
	v_lshl_add_u64 v[80:81], v[80:81], 0, v[180:181]
	s_waitcnt vmcnt(4)
	v_mov_b32_e32 v84, v218
	v_mov_b32_e32 v85, v219
	v_mov_b32_e32 v86, v220
	v_mov_b32_e32 v87, v221
	v_mov_b32_e32 v80, v222
	v_mov_b32_e32 v81, v223
	v_mov_b32_e32 v82, v224
	v_mov_b32_e32 v83, v225
	v_add_u32_e32 v244, 0xb0000, v200
	global_load_dwordx4 v[218:221], v244, s[82:83]
	global_load_dwordx4 v[222:225], v244, s[82:83] offset:256
	s_nop 0
	v_lshlrev_b32_e32 v174, 16, v100
	v_and_b32_e32 v175, 0xffff0000, v100
	v_lshlrev_b32_e32 v100, 16, v101
	v_and_b32_e32 v101, 0xffff0000, v101
	v_pk_add_f32 v[78:79], v[78:79], v[100:101]
	v_pk_add_f32 v[76:77], v[76:77], v[174:175]
	v_lshlrev_b32_e32 v192, 16, v98
	v_and_b32_e32 v193, 0xffff0000, v98
	v_lshlrev_b32_e32 v194, 16, v99
	v_and_b32_e32 v195, 0xffff0000, v99
	v_mul_f32_e32 v98, v77, v77
	v_mul_f32_e32 v99, v79, v79
	v_lshlrev_b32_e32 v176, 16, v102
	v_and_b32_e32 v177, 0xffff0000, v102
	v_lshlrev_b32_e32 v102, 16, v103
	v_and_b32_e32 v103, 0xffff0000, v103
	v_fmac_f32_e32 v98, v76, v76
	v_fmac_f32_e32 v99, v78, v78
	v_add_f32_e32 v100, v98, v99
	v_pk_add_f32 v[74:75], v[74:75], v[102:103]
	v_pk_add_f32 v[98:99], v[72:73], v[176:177]
	v_mul_f32_e32 v73, v75, v75
	v_mul_f32_e32 v72, v99, v99
	v_lshlrev_b32_e32 v178, 16, v96
	v_and_b32_e32 v179, 0xffff0000, v96
	v_lshlrev_b32_e32 v96, 16, v97
	v_and_b32_e32 v97, 0xffff0000, v97
	v_fmac_f32_e32 v72, v98, v98
	v_fmac_f32_e32 v73, v74, v74
	v_add_f32_e32 v72, v72, v73
	v_pk_add_f32 v[96:97], v[70:71], v[96:97]
	v_pk_add_f32 v[102:103], v[68:69], v[178:179]
	v_add_f32_e32 v72, v100, v72
	v_mul_f32_e32 v68, v103, v103
	v_mul_f32_e32 v69, v97, v97
	v_pk_add_f32 v[100:101], v[66:67], v[194:195]
	v_pk_add_f32 v[174:175], v[64:65], v[192:193]
	v_fmac_f32_e32 v68, v102, v102
	v_fmac_f32_e32 v69, v96, v96
	v_mul_f32_e32 v64, v175, v175
	v_mul_f32_e32 v65, v101, v101
	v_add_f32_e32 v68, v68, v69
	v_fmac_f32_e32 v64, v174, v174
	v_fmac_f32_e32 v65, v100, v100
	v_add_f32_e32 v68, v72, v68
	v_add_f32_e32 v64, v64, v65
	v_add_f32_e32 v64, v64, v68
	ds_bpermute_b32 v65, v182, v64
	s_waitcnt lgkmcnt(0)
	v_add_f32_e32 v64, v64, v65
	ds_bpermute_b32 v65, v183, v64
	s_and_saveexec_b64 s[0:1], s[4:5]
	s_cbranch_execz .LBB0_1135
	v_lshl_add_u64 v[66:67], v[104:105], 2, s[16:17]
	s_waitcnt lgkmcnt(0)
	v_add_f32_e32 v64, v64, v65
	v_mov_b32_e32 v239, v64
	v_lshlrev_b32_e32 v231, 2, v104
; #define EDN_LOAD(P, row) do { const float* s_ = H1 + (size_t)(row) * 2048 + col0; P[0][0] = *(const f32x4*)s_; P[0][1] = *(const f32x4*)(s_ + 4); P[1][0] = *(const f32x4*)(s_ + 128); P[1][1] = *(const f32x4*)(s_ + 132); } while (0)
;     __device__ __forceinline__ void operator()(const pg8::f32x4 (&acc)[2][2][4][2], const pg8::Unit& u, int wr, int wc, int fr, int fq) const {
;     ...
;         for (int g = 0; g < 8; ++g) {
;             const int ai = g >> 2, m = g & 3, row = row0 + ai * 128 + m * 16;
;             if (g < 7) { const int row2 = row0 + ((g + 1) >> 2) * 128 + ((g + 1) & 3) * 16; if (g & 1) EDN_LOAD(pa, row2); else EDN_LOAD(pb, row2); }
;             float s = 0.f;
; #pragma unroll
;             for (int bj = 0; bj < 2; ++bj)
; #pragma unroll
;                 for (int n = 0; n < 2; ++n) { const f32x4 hv = h[ai][bj][m][n] + ((g & 1) ? pb[bj][n] : pa[bj][n]); h[ai][bj][m][n] = hv; s += (hv[0] * hv[0] + hv[1] * hv[1]) + (hv[2] * hv[2] + hv[3] * hv[3]); }
;             s += __shfl_xor(s, 16); s += __shfl_xor(s, 32);
;             if (fq == 0) atomicAdd(ss + row, s);
.LBB0_1135:
	s_or_b64 exec, exec, s[0:1]
	v_or_b32_e32 v72, 16, v88
	v_ashrrev_i32_e32 v73, 31, v72
	s_waitcnt lgkmcnt(0)
	v_lshlrev_b64 v[64:65], 12, v[72:73]
	v_lshl_add_u64 v[64:65], s[82:83], 0, v[64:65]
	v_lshl_add_u64 v[64:65], v[64:65], 0, v[180:181]
	s_waitcnt vmcnt(4)
	v_mov_b32_e32 v68, v202
	v_mov_b32_e32 v69, v203
	v_mov_b32_e32 v70, v204
	v_mov_b32_e32 v71, v205
	v_mov_b32_e32 v64, v206
	v_mov_b32_e32 v65, v207
	v_mov_b32_e32 v66, v208
	v_mov_b32_e32 v67, v209
	s_nop 0
	v_lshlrev_b32_e32 v176, 16, v84
	v_and_b32_e32 v177, 0xffff0000, v84
	v_lshlrev_b32_e32 v84, 16, v85
	v_and_b32_e32 v85, 0xffff0000, v85
	v_pk_add_f32 v[62:63], v[62:63], v[84:85]
	v_pk_add_f32 v[60:61], v[60:61], v[176:177]
	v_lshlrev_b32_e32 v194, 16, v82
	v_and_b32_e32 v195, 0xffff0000, v82
	v_lshlrev_b32_e32 v196, 16, v83
	v_and_b32_e32 v197, 0xffff0000, v83
	v_mul_f32_e32 v82, v61, v61
	v_mul_f32_e32 v83, v63, v63
	v_lshlrev_b32_e32 v178, 16, v86
	v_and_b32_e32 v179, 0xffff0000, v86
	v_lshlrev_b32_e32 v86, 16, v87
	v_and_b32_e32 v87, 0xffff0000, v87
	v_fmac_f32_e32 v82, v60, v60
	v_fmac_f32_e32 v83, v62, v62
	v_add_f32_e32 v84, v82, v83
	v_pk_add_f32 v[58:59], v[58:59], v[86:87]
	v_pk_add_f32 v[82:83], v[56:57], v[178:179]
	v_mul_f32_e32 v57, v59, v59
	v_mul_f32_e32 v56, v83, v83
	v_lshlrev_b32_e32 v192, 16, v80
	v_and_b32_e32 v193, 0xffff0000, v80
	v_lshlrev_b32_e32 v80, 16, v81
	v_and_b32_e32 v81, 0xffff0000, v81
	v_fmac_f32_e32 v56, v82, v82
	v_fmac_f32_e32 v57, v58, v58
	v_add_f32_e32 v56, v56, v57
	v_pk_add_f32 v[80:81], v[54:55], v[80:81]
	v_pk_add_f32 v[86:87], v[52:53], v[192:193]
	v_add_f32_e32 v56, v84, v56
	v_mul_f32_e32 v52, v87, v87
	v_mul_f32_e32 v53, v81, v81
	v_pk_add_f32 v[84:85], v[50:51], v[196:197]
	v_pk_add_f32 v[176:177], v[48:49], v[194:195]
	v_fmac_f32_e32 v52, v86, v86
	v_fmac_f32_e32 v53, v80, v80
	v_mul_f32_e32 v48, v177, v177
	v_mul_f32_e32 v49, v85, v85
	v_add_f32_e32 v52, v52, v53
	v_fmac_f32_e32 v48, v176, v176
	v_fmac_f32_e32 v49, v84, v84
	v_add_f32_e32 v52, v56, v52
	v_add_f32_e32 v48, v48, v49
	v_add_f32_e32 v48, v48, v52
	ds_bpermute_b32 v49, v182, v48
	s_waitcnt lgkmcnt(0)
	v_add_f32_e32 v48, v48, v49
	ds_bpermute_b32 v49, v183, v48
	s_and_saveexec_b64 s[0:1], s[4:5]
	s_cbranch_execz .LBB0_1137
	v_lshl_add_u64 v[50:51], v[88:89], 2, s[16:17]
	s_waitcnt lgkmcnt(0)
	v_add_f32_e32 v48, v48, v49
	v_mov_b32_e32 v240, v48
	v_lshlrev_b32_e32 v232, 2, v88
.LBB0_1137:
	s_or_b64 exec, exec, s[0:1]
	v_or_b32_e32 v56, 32, v88
	v_ashrrev_i32_e32 v57, 31, v56
	s_waitcnt lgkmcnt(0)
	v_lshlrev_b64 v[48:49], 12, v[56:57]
	v_lshl_add_u64 v[48:49], s[82:83], 0, v[48:49]
	v_mov_b32_e32 v181, v145
	v_lshl_add_u64 v[48:49], v[48:49], 0, v[180:181]
	s_waitcnt vmcnt(2)
	v_mov_b32_e32 v52, v210
	v_mov_b32_e32 v53, v211
	v_mov_b32_e32 v54, v212
	v_mov_b32_e32 v55, v213
	v_mov_b32_e32 v48, v214
	v_mov_b32_e32 v49, v215
	v_mov_b32_e32 v50, v216
	v_mov_b32_e32 v51, v217
	s_nop 0
	v_lshlrev_b32_e32 v178, 16, v68
	v_and_b32_e32 v179, 0xffff0000, v68
	v_lshlrev_b32_e32 v68, 16, v69
	v_and_b32_e32 v69, 0xffff0000, v69
	v_pk_add_f32 v[46:47], v[46:47], v[68:69]
	v_pk_add_f32 v[44:45], v[44:45], v[178:179]
	v_lshlrev_b32_e32 v196, 16, v66
	v_and_b32_e32 v197, 0xffff0000, v66
	v_lshlrev_b32_e32 v198, 16, v67
	v_and_b32_e32 v199, 0xffff0000, v67
	v_mul_f32_e32 v66, v45, v45
	v_mul_f32_e32 v67, v47, v47
	v_lshlrev_b32_e32 v192, 16, v70
	v_and_b32_e32 v193, 0xffff0000, v70
	v_lshlrev_b32_e32 v70, 16, v71
	v_and_b32_e32 v71, 0xffff0000, v71
	v_fmac_f32_e32 v66, v44, v44
	v_fmac_f32_e32 v67, v46, v46
	v_add_f32_e32 v68, v66, v67
	v_pk_add_f32 v[42:43], v[42:43], v[70:71]
	v_pk_add_f32 v[66:67], v[40:41], v[192:193]
	v_mul_f32_e32 v41, v43, v43
	v_mul_f32_e32 v40, v67, v67
	v_lshlrev_b32_e32 v194, 16, v64
	v_and_b32_e32 v195, 0xffff0000, v64
	v_lshlrev_b32_e32 v64, 16, v65
	v_and_b32_e32 v65, 0xffff0000, v65
	v_fmac_f32_e32 v40, v66, v66
	v_fmac_f32_e32 v41, v42, v42
	v_add_f32_e32 v40, v40, v41
	v_pk_add_f32 v[64:65], v[38:39], v[64:65]
	v_pk_add_f32 v[70:71], v[36:37], v[194:195]
	v_add_f32_e32 v40, v68, v40
	v_mul_f32_e32 v36, v71, v71
	v_mul_f32_e32 v37, v65, v65
	v_pk_add_f32 v[68:69], v[34:35], v[198:199]
	v_pk_add_f32 v[178:179], v[32:33], v[196:197]
	v_fmac_f32_e32 v36, v70, v70
	v_fmac_f32_e32 v37, v64, v64
	v_mul_f32_e32 v32, v179, v179
	v_mul_f32_e32 v33, v69, v69
	v_add_f32_e32 v36, v36, v37
	v_fmac_f32_e32 v32, v178, v178
	v_fmac_f32_e32 v33, v68, v68
	v_add_f32_e32 v36, v40, v36
	v_add_f32_e32 v32, v32, v33
	v_add_f32_e32 v32, v32, v36
	ds_bpermute_b32 v33, v182, v32
	s_waitcnt lgkmcnt(0)
	v_add_f32_e32 v32, v32, v33
	ds_bpermute_b32 v33, v183, v32
	s_and_saveexec_b64 s[0:1], s[4:5]
	s_cbranch_execz .LBB0_1139
	v_lshl_add_u64 v[34:35], v[72:73], 2, s[16:17]
	s_waitcnt lgkmcnt(0)
	v_add_f32_e32 v32, v32, v33
	v_mov_b32_e32 v241, v32
	v_lshlrev_b32_e32 v233, 2, v72
; #define EDN_LOAD(P, row) do { const float* s_ = H1 + (size_t)(row) * 2048 + col0; P[0][0] = *(const f32x4*)s_; P[0][1] = *(const f32x4*)(s_ + 4); P[1][0] = *(const f32x4*)(s_ + 128); P[1][1] = *(const f32x4*)(s_ + 132); } while (0)
;     __device__ __forceinline__ void operator()(const pg8::f32x4 (&acc)[2][2][4][2], const pg8::Unit& u, int wr, int wc, int fr, int fq) const {
;     ...
;         for (int g = 0; g < 8; ++g) {
;             const int ai = g >> 2, m = g & 3, row = row0 + ai * 128 + m * 16;
;             if (g < 7) { const int row2 = row0 + ((g + 1) >> 2) * 128 + ((g + 1) & 3) * 16; if (g & 1) EDN_LOAD(pa, row2); else EDN_LOAD(pb, row2); }
;             float s = 0.f;
; #pragma unroll
;             for (int bj = 0; bj < 2; ++bj)
; #pragma unroll
;                 for (int n = 0; n < 2; ++n) { const f32x4 hv = h[ai][bj][m][n] + ((g & 1) ? pb[bj][n] : pa[bj][n]); h[ai][bj][m][n] = hv; s += (hv[0] * hv[0] + hv[1] * hv[1]) + (hv[2] * hv[2] + hv[3] * hv[3]); }
;             s += __shfl_xor(s, 16); s += __shfl_xor(s, 32);
;             if (fq == 0) atomicAdd(ss + row, s);
.LBB0_1139:
	s_or_b64 exec, exec, s[0:1]
	v_or_b32_e32 v40, 48, v88
	v_ashrrev_i32_e32 v41, 31, v40
	s_waitcnt lgkmcnt(0)
	v_lshlrev_b64 v[32:33], 12, v[40:41]
	v_lshl_add_u64 v[32:33], s[82:83], 0, v[32:33]
	v_lshl_add_u64 v[32:33], v[32:33], 0, v[180:181]
	s_waitcnt vmcnt(0)
	v_mov_b32_e32 v36, v218
	v_mov_b32_e32 v37, v219
	v_mov_b32_e32 v38, v220
	v_mov_b32_e32 v39, v221
	v_mov_b32_e32 v32, v222
	v_mov_b32_e32 v33, v223
	v_mov_b32_e32 v34, v224
	v_mov_b32_e32 v35, v225
	s_nop 0
	v_lshlrev_b32_e32 v180, 16, v52
	v_and_b32_e32 v181, 0xffff0000, v52
	v_lshlrev_b32_e32 v52, 16, v53
	v_and_b32_e32 v53, 0xffff0000, v53
	v_pk_add_f32 v[30:31], v[30:31], v[52:53]
	v_pk_add_f32 v[28:29], v[28:29], v[180:181]
	v_lshlrev_b32_e32 v192, 16, v54
	v_and_b32_e32 v193, 0xffff0000, v54
	v_lshlrev_b32_e32 v54, 16, v55
	v_and_b32_e32 v55, 0xffff0000, v55
	v_lshlrev_b32_e32 v194, 16, v48
	v_and_b32_e32 v195, 0xffff0000, v48
	v_lshlrev_b32_e32 v48, 16, v49
	v_and_b32_e32 v49, 0xffff0000, v49
	v_mul_f32_e32 v52, v29, v29
	v_mul_f32_e32 v53, v31, v31
	v_fmac_f32_e32 v52, v28, v28
	v_fmac_f32_e32 v53, v30, v30
	v_pk_add_f32 v[26:27], v[26:27], v[54:55]
	v_pk_add_f32 v[24:25], v[24:25], v[192:193]
	v_pk_add_f32 v[22:23], v[22:23], v[48:49]
	v_pk_add_f32 v[20:21], v[20:21], v[194:195]
	v_lshlrev_b32_e32 v196, 16, v50
	v_and_b32_e32 v197, 0xffff0000, v50
	v_lshlrev_b32_e32 v50, 16, v51
	v_and_b32_e32 v51, 0xffff0000, v51
	v_add_f32_e32 v52, v52, v53
	v_mul_f32_e32 v53, v25, v25
	v_mul_f32_e32 v54, v27, v27
	v_mul_f32_e32 v48, v21, v21
	v_mul_f32_e32 v49, v23, v23
	v_fmac_f32_e32 v53, v24, v24
	v_fmac_f32_e32 v54, v26, v26
	v_fmac_f32_e32 v48, v20, v20
	v_fmac_f32_e32 v49, v22, v22
	v_pk_add_f32 v[18:19], v[18:19], v[50:51]
	v_pk_add_f32 v[16:17], v[16:17], v[196:197]
	v_add_f32_e32 v53, v53, v54
	v_add_f32_e32 v48, v48, v49
	v_mul_f32_e32 v49, v17, v17
	v_mul_f32_e32 v50, v19, v19
	v_add_f32_e32 v52, v52, v53
	v_fmac_f32_e32 v49, v16, v16
	v_fmac_f32_e32 v50, v18, v18
	v_add_f32_e32 v48, v52, v48
	v_add_f32_e32 v49, v49, v50
	v_add_f32_e32 v48, v49, v48
	ds_bpermute_b32 v49, v182, v48
	s_waitcnt lgkmcnt(0)
	v_add_f32_e32 v48, v48, v49
	ds_bpermute_b32 v49, v183, v48
	s_and_saveexec_b64 s[0:1], s[4:5]
	s_cbranch_execz .LBB0_1141
	v_lshl_add_u64 v[50:51], v[56:57], 2, s[16:17]
	s_waitcnt lgkmcnt(0)
	v_add_f32_e32 v48, v48, v49
	v_mov_b32_e32 v242, v48
	v_lshlrev_b32_e32 v234, 2, v56
.LBB0_1141:
	s_or_b64 exec, exec, s[0:1]
	v_lshlrev_b32_e32 v48, 16, v36
	s_waitcnt lgkmcnt(0)
	v_and_b32_e32 v49, 0xffff0000, v36
	v_lshlrev_b32_e32 v36, 16, v37
	v_and_b32_e32 v37, 0xffff0000, v37
	v_lshlrev_b32_e32 v50, 16, v38
	v_and_b32_e32 v51, 0xffff0000, v38
	v_lshlrev_b32_e32 v38, 16, v39
	v_and_b32_e32 v39, 0xffff0000, v39
	v_lshlrev_b32_e32 v52, 16, v32
	v_and_b32_e32 v53, 0xffff0000, v32
	v_lshlrev_b32_e32 v54, 16, v33
	v_and_b32_e32 v55, 0xffff0000, v33
	v_lshlrev_b32_e32 v180, 16, v34
	v_and_b32_e32 v181, 0xffff0000, v34
	v_lshlrev_b32_e32 v192, 16, v35
	v_and_b32_e32 v193, 0xffff0000, v35
	v_pk_add_f32 v[32:33], v[14:15], v[36:37]
	v_pk_add_f32 v[36:37], v[12:13], v[48:49]
	v_pk_add_f32 v[34:35], v[10:11], v[38:39]
	v_pk_add_f32 v[48:49], v[8:9], v[50:51]
	v_mul_f32_e32 v12, v37, v37
	v_mul_f32_e32 v13, v33, v33
	v_mul_f32_e32 v8, v49, v49
	v_mul_f32_e32 v9, v35, v35
	v_pk_add_f32 v[38:39], v[6:7], v[54:55]
	v_pk_add_f32 v[52:53], v[4:5], v[52:53]
	v_fmac_f32_e32 v12, v36, v36
	v_fmac_f32_e32 v13, v32, v32
	v_fmac_f32_e32 v8, v48, v48
	v_fmac_f32_e32 v9, v34, v34
	v_mul_f32_e32 v4, v53, v53
	v_mul_f32_e32 v5, v39, v39
	v_pk_add_f32 v[50:51], v[2:3], v[192:193]
	v_pk_add_f32 v[54:55], v[0:1], v[180:181]
	v_add_f32_e32 v12, v12, v13
	v_add_f32_e32 v8, v8, v9
	v_fmac_f32_e32 v4, v52, v52
	v_fmac_f32_e32 v5, v38, v38
	v_mul_f32_e32 v0, v55, v55
	v_mul_f32_e32 v1, v51, v51
	v_add_f32_e32 v8, v12, v8
	v_add_f32_e32 v4, v4, v5
	v_fmac_f32_e32 v0, v54, v54
	v_fmac_f32_e32 v1, v50, v50
	v_add_f32_e32 v4, v8, v4
	v_add_f32_e32 v0, v0, v1
	v_add_f32_e32 v0, v0, v4
	ds_bpermute_b32 v1, v182, v0
	s_waitcnt lgkmcnt(0)
	v_add_f32_e32 v0, v0, v1
	ds_bpermute_b32 v1, v183, v0
	s_and_saveexec_b64 s[0:1], s[4:5]
	s_cbranch_execz .LBB0_1143
	v_lshl_add_u64 v[2:3], v[40:41], 2, s[16:17]
	s_waitcnt lgkmcnt(0)
	v_add_f32_e32 v0, v0, v1
	v_mov_b32_e32 v243, v0
	v_lshlrev_b32_e32 v235, 2, v40
	global_atomic_add_f32 v228, v236, s[16:17]
	global_atomic_add_f32 v229, v237, s[16:17]
	global_atomic_add_f32 v230, v238, s[16:17]
	global_atomic_add_f32 v231, v239, s[16:17]
	global_atomic_add_f32 v232, v240, s[16:17]
	global_atomic_add_f32 v233, v241, s[16:17]
	global_atomic_add_f32 v234, v242, s[16:17]
	global_atomic_add_f32 v235, v243, s[16:17]

;     __device__ __forceinline__ void operator()(const pg8::f32x4 (&acc)[2][2][4][2], const pg8::Unit& u, int wr, int wc, int fr, int fq) const {
;     ...
;         asm volatile("s_waitcnt vmcnt(0)" ::: "memory");
;         unsigned* cw = cnt + 64 * u.pm;
;         if ((threadIdx.x & 63) == 0) __hip_atomic_fetch_add(cw, 1u, __ATOMIC_RELAXED, __HIP_MEMORY_SCOPE_AGENT);
;         f32x4 gv[2][2];
; #pragma unroll
;         for (int bj = 0; bj < 2; ++bj) { gv[bj][0] = *(const f32x4*)(fg + col0 + bj * 128); gv[bj][1] = *(const f32x4*)(fg + col0 + bj * 128 + 4); }
;         { unsigned spins = 0;
;           while ((unsigned)__builtin_amdgcn_readfirstlane((int)__hip_atomic_load(cw, __ATOMIC_RELAXED, __HIP_MEMORY_SCOPE_AGENT)) < 64u) { __builtin_amdgcn_s_sleep(2); if (++spins > (1u << 20)) break; } }
;         __builtin_amdgcn_fence(__ATOMIC_ACQUIRE, "agent");
.LBB0_1146:
	s_or_b64 exec, exec, s[2:3]
	buffer_inv sc1
	v_lshl_add_u64 v[4:5], v[144:145], 2, s[56:57]
	global_load_dwordx4 v[8:11], v[4:5], off offset:16
	global_load_dwordx4 v[12:15], v[4:5], off
	s_waitcnt lgkmcnt(0)
	global_load_dwordx4 v[0:3], v[4:5], off offset:528
	s_nop 0
	global_load_dwordx4 v[4:7], v[4:5], off offset:512
	s_mov_b32 s10, 0x100001
	s_branch .LBB0_1148

;     __device__ __forceinline__ void operator()(const pg8::f32x4 (&acc)[2][2][4][2], const pg8::Unit& u, int wr, int wc, int fr, int fq) const {
;     ...
;         float tot[8];
; #pragma unroll
;         for (int g = 0; g < 8; ++g) tot[g] = __hip_atomic_load(ss + row0 + (g >> 2) * 128 + (g & 3) * 16, __ATOMIC_RELAXED, __HIP_MEMORY_SCOPE_AGENT);
; #pragma unroll
;         for (int g = 0; g < 8; ++g) {
;             const int ai = g >> 2, m = g & 3, row = row0 + ai * 128 + m * 16;
;             const float r = rsqrtf(tot[g] * (1.f / 2048.f) + EPS);
;             float* o = out + (size_t)row * 2048 + col0;
; #pragma unroll
;             for (int bj = 0; bj < 2; ++bj)
; #pragma unroll
;                 for (int n = 0; n < 2; ++n) *(f32x4*)(o + bj * 128 + 4 * n) = h[ai][bj][m][n] * r * gv[bj][n];
;         }
.LBB0_1150:
	global_load_dword v193, v[170:171], off sc1
	global_load_dword v192, v[170:171], off offset:64 sc1
	global_load_dword v195, v[170:171], off offset:128 sc1
	global_load_dword v194, v[170:171], off offset:192 sc1
	global_load_dword v183, v[170:171], off offset:512 sc1
	global_load_dword v182, v[170:171], off offset:576 sc1
	global_load_dword v181, v[170:171], off offset:640 sc1
	global_load_dword v180, v[170:171], off offset:704 sc1
	v_lshlrev_b64 v[160:161], 13, v[160:161]
	v_lshlrev_b64 v[196:197], 13, v[164:165]
	v_lshlrev_b64 v[164:165], 2, v[144:145]
	v_mov_b64_e32 v[170:171], s[24:25]
	v_lshl_add_u64 v[160:161], s[58:59], 0, v[160:161]
	v_lshl_add_u64 v[198:199], v[160:161], 0, v[164:165]
	v_lshlrev_b64 v[166:167], 13, v[166:167]
	v_lshl_add_u64 v[166:167], s[58:59], 0, v[166:167]
	v_lshl_add_u64 v[196:197], s[58:59], 0, v[196:197]
	v_lshl_add_u64 v[196:197], v[196:197], 0, v[164:165]
	s_waitcnt vmcnt(6)
	v_pk_fma_f32 v[160:161], v[192:193], s[22:23], v[170:171] op_sel_hi:[1,0,0]
	s_nop 0
	v_mul_f32_e32 v144, 0x4b800000, v161
	s_waitcnt vmcnt(4)
	v_pk_fma_f32 v[192:193], v[194:195], s[22:23], v[170:171] op_sel_hi:[1,0,0]
	v_cmp_gt_f32_e32 vcc, s48, v161
	v_mul_f32_e32 v195, 0x4b800000, v193
	v_cmp_gt_f32_e64 s[10:11], s48, v193
	v_mul_f32_e32 v194, 0x4b800000, v160
	v_cndmask_b32_e32 v144, v161, v144, vcc
	v_cmp_gt_f32_e64 s[0:1], s48, v160
	v_cndmask_b32_e64 v161, v193, v195, s[10:11]
	v_rsq_f32_e32 v144, v144
	v_cndmask_b32_e64 v160, v160, v194, s[0:1]
	v_rsq_f32_e32 v161, v161
	v_rsq_f32_e32 v160, v160
	v_lshl_add_u64 v[194:195], v[166:167], 0, v[164:165]
	v_mul_f32_e32 v166, 0x45800000, v144
	v_mul_f32_e32 v193, 0x45800000, v161
	v_mul_f32_e32 v167, 0x45800000, v160
	v_cndmask_b32_e32 v144, v144, v166, vcc
	v_cndmask_b32_e64 v200, v161, v193, s[10:11]
	v_cndmask_b32_e64 v160, v160, v167, s[0:1]
	v_pk_mul_f32 v[124:125], v[124:125], v[144:145] op_sel_hi:[1,0]
	v_pk_mul_f32 v[126:127], v[126:127], v[144:145] op_sel_hi:[1,0]
	v_pk_mul_f32 v[94:95], v[94:95], v[200:201] op_sel_hi:[1,0]
	v_pk_mul_f32 v[120:121], v[120:121], v[144:145] op_sel_hi:[1,0]
	v_pk_mul_f32 v[122:123], v[122:123], v[144:145] op_sel_hi:[1,0]
	v_pk_mul_f32 v[156:157], v[156:157], v[144:145] op_sel_hi:[1,0]
	v_pk_mul_f32 v[154:155], v[154:155], v[144:145] op_sel_hi:[1,0]
	v_pk_mul_f32 v[162:163], v[162:163], v[144:145] op_sel_hi:[1,0]
	v_pk_mul_f32 v[158:159], v[158:159], v[144:145] op_sel_hi:[1,0]
	v_pk_mul_f32 v[166:167], v[108:109], v[160:161] op_sel_hi:[1,0]
	v_pk_mul_f32 v[202:203], v[110:111], v[160:161] op_sel_hi:[1,0]
	v_pk_mul_f32 v[204:205], v[128:129], v[160:161] op_sel_hi:[1,0]
	v_pk_mul_f32 v[128:129], v[106:107], v[160:161] op_sel_hi:[1,0]
	v_pk_mul_f32 v[206:207], v[132:133], v[160:161] op_sel_hi:[1,0]
	v_pk_mul_f32 v[130:131], v[130:131], v[160:161] op_sel_hi:[1,0]
	v_pk_mul_f32 v[168:169], v[168:169], v[160:161] op_sel_hi:[1,0]
	v_pk_mul_f32 v[134:135], v[134:135], v[160:161] op_sel_hi:[1,0]
	v_pk_mul_f32 v[208:209], v[114:115], v[200:201] op_sel_hi:[1,0]
	v_pk_mul_f32 v[210:211], v[118:119], v[200:201] op_sel_hi:[1,0]
	v_pk_mul_f32 v[212:213], v[112:113], v[200:201] op_sel_hi:[1,0]
	v_pk_mul_f32 v[172:173], v[172:173], v[200:201] op_sel_hi:[1,0]
	v_pk_mul_f32 v[214:215], v[116:117], v[200:201] op_sel_hi:[1,0]
	v_pk_mul_f32 v[108:109], v[14:15], v[126:127]
	v_pk_mul_f32 v[106:107], v[12:13], v[124:125]
	v_pk_mul_f32 v[160:161], v[14:15], v[94:95]
	v_pk_mul_f32 v[94:95], v[92:93], v[200:201] op_sel_hi:[1,0]
	v_mul_f32_e32 v92, 0x4b800000, v192
	v_cmp_gt_f32_e32 vcc, s48, v192
	v_pk_mul_f32 v[112:113], v[10:11], v[122:123]
	v_pk_mul_f32 v[110:111], v[8:9], v[120:121]
	v_pk_mul_f32 v[116:117], v[6:7], v[154:155]
	v_pk_mul_f32 v[114:115], v[4:5], v[156:157]
	v_pk_mul_f32 v[120:121], v[2:3], v[158:159]
	v_pk_mul_f32 v[118:119], v[0:1], v[162:163]
	v_pk_mul_f32 v[124:125], v[14:15], v[202:203]
	v_pk_mul_f32 v[122:123], v[12:13], v[166:167]
	v_pk_mul_f32 v[128:129], v[10:11], v[128:129]
	v_pk_mul_f32 v[126:127], v[8:9], v[204:205]
	v_pk_mul_f32 v[132:133], v[6:7], v[130:131]
	v_pk_mul_f32 v[130:131], v[4:5], v[206:207]
	v_pk_mul_f32 v[156:157], v[2:3], v[134:135]
	v_pk_mul_f32 v[154:155], v[0:1], v[168:169]
	v_pk_mul_f32 v[158:159], v[12:13], v[208:209]
	v_pk_mul_f32 v[168:169], v[10:11], v[212:213]
	v_pk_mul_f32 v[166:167], v[8:9], v[210:211]
	global_store_dwordx4 v[196:197], v[106:109], off
	global_store_dwordx4 v[196:197], v[110:113], off offset:16
	global_store_dwordx4 v[196:197], v[114:117], off offset:512
	global_store_dwordx4 v[196:197], v[118:121], off offset:528
	global_store_dwordx4 v[198:199], v[122:125], off
	global_store_dwordx4 v[198:199], v[126:129], off offset:16
	global_store_dwordx4 v[198:199], v[130:133], off offset:512
	global_store_dwordx4 v[198:199], v[154:157], off offset:528
	global_store_dwordx4 v[194:195], v[158:161], off
	global_store_dwordx4 v[194:195], v[166:169], off offset:16
	v_pk_mul_f32 v[108:109], v[6:7], v[214:215]
	v_pk_mul_f32 v[106:107], v[4:5], v[172:173]
	v_cndmask_b32_e32 v92, v192, v92, vcc
	global_store_dwordx4 v[194:195], v[106:109], off offset:512
	v_pk_mul_f32 v[90:91], v[90:91], v[200:201] op_sel_hi:[1,0]
	s_mov_b64 s[0:1], -1
	v_rsq_f32_e32 v106, v92
	v_pk_mul_f32 v[92:93], v[2:3], v[90:91]
	v_pk_mul_f32 v[90:91], v[0:1], v[94:95]
	global_store_dwordx4 v[194:195], v[90:93], off offset:528
	s_nop 1
	v_mul_f32_e32 v90, 0x45800000, v106
	v_cndmask_b32_e32 v90, v106, v90, vcc
	v_lshlrev_b64 v[92:93], 13, v[104:105]
	v_lshl_add_u64 v[92:93], s[58:59], 0, v[92:93]
	v_pk_mul_f32 v[76:77], v[76:77], v[90:91] op_sel_hi:[1,0]
	v_pk_mul_f32 v[78:79], v[78:79], v[90:91] op_sel_hi:[1,0]
	v_lshl_add_u64 v[92:93], v[92:93], 0, v[164:165]
	v_pk_mul_f32 v[78:79], v[14:15], v[78:79]
	v_pk_mul_f32 v[76:77], v[12:13], v[76:77]
	global_store_dwordx4 v[92:93], v[76:79], off
	v_pk_mul_f32 v[74:75], v[74:75], v[90:91] op_sel_hi:[1,0]
	s_nop 0
	v_pk_mul_f32 v[78:79], v[98:99], v[90:91] op_sel_hi:[1,0]
	v_pk_mul_f32 v[76:77], v[10:11], v[74:75]
	v_pk_mul_f32 v[74:75], v[8:9], v[78:79]
	global_store_dwordx4 v[92:93], v[74:77], off offset:16
	s_nop 1
	v_pk_mul_f32 v[74:75], v[102:103], v[90:91] op_sel_hi:[1,0]
	v_pk_mul_f32 v[76:77], v[96:97], v[90:91] op_sel_hi:[1,0]
	v_pk_mul_f32 v[74:75], v[4:5], v[74:75]
	v_pk_mul_f32 v[76:77], v[6:7], v[76:77]
	global_store_dwordx4 v[92:93], v[74:77], off offset:512
	s_nop 1
	v_pk_mul_f32 v[74:75], v[174:175], v[90:91] op_sel_hi:[1,0]
	v_pk_mul_f32 v[76:77], v[100:101], v[90:91] op_sel_hi:[1,0]
	v_pk_mul_f32 v[74:75], v[0:1], v[74:75]
	v_pk_mul_f32 v[76:77], v[2:3], v[76:77]
	global_store_dwordx4 v[92:93], v[74:77], off offset:528
	s_waitcnt vmcnt(18)
;     __device__ __forceinline__ void operator()(const pg8::f32x4 (&acc)[2][2][4][2], const pg8::Unit& u, int wr, int wc, int fr, int fq) const {
;     ...
; #pragma unroll
;         for (int g = 0; g < 8; ++g) {
;             const int ai = g >> 2, m = g & 3, row = row0 + ai * 128 + m * 16;
;             const float r = rsqrtf(tot[g] * (1.f / 2048.f) + EPS);
;             float* o = out + (size_t)row * 2048 + col0;
; #pragma unroll
;             for (int bj = 0; bj < 2; ++bj)
; #pragma unroll
;                 for (int n = 0; n < 2; ++n) *(f32x4*)(o + bj * 128 + 4 * n) = h[ai][bj][m][n] * r * gv[bj][n];
;         }
	s_nop 0
	v_pk_fma_f32 v[74:75], v[182:183], s[22:23], v[170:171] op_sel_hi:[1,0,0]
	s_nop 0
	v_mul_f32_e32 v76, 0x4b800000, v75
	v_cmp_gt_f32_e32 vcc, s48, v75
	s_nop 1
	v_cndmask_b32_e32 v75, v75, v76, vcc
	v_rsq_f32_e32 v75, v75
	v_lshlrev_b64 v[76:77], 13, v[88:89]
	v_lshl_add_u64 v[76:77], s[58:59], 0, v[76:77]
	v_lshl_add_u64 v[76:77], v[76:77], 0, v[164:165]
	v_mul_f32_e32 v78, 0x45800000, v75
	v_cndmask_b32_e32 v78, v75, v78, vcc
	v_pk_mul_f32 v[60:61], v[60:61], v[78:79] op_sel_hi:[1,0]
	v_pk_mul_f32 v[62:63], v[62:63], v[78:79] op_sel_hi:[1,0]
	v_pk_mul_f32 v[60:61], v[12:13], v[60:61]
	v_pk_mul_f32 v[62:63], v[14:15], v[62:63]
	global_store_dwordx4 v[76:77], v[60:63], off
	v_pk_mul_f32 v[58:59], v[58:59], v[78:79] op_sel_hi:[1,0]
	v_cmp_gt_f32_e32 vcc, s48, v74
	v_pk_mul_f32 v[62:63], v[82:83], v[78:79] op_sel_hi:[1,0]
	v_pk_mul_f32 v[60:61], v[10:11], v[58:59]
	v_pk_mul_f32 v[58:59], v[8:9], v[62:63]
	v_mul_f32_e32 v62, 0x4b800000, v74
	v_cndmask_b32_e32 v62, v74, v62, vcc
	global_store_dwordx4 v[76:77], v[58:61], off offset:16
	v_rsq_f32_e32 v62, v62
	s_nop 0
	v_pk_mul_f32 v[58:59], v[86:87], v[78:79] op_sel_hi:[1,0]
	v_pk_mul_f32 v[60:61], v[80:81], v[78:79] op_sel_hi:[1,0]
	v_pk_mul_f32 v[58:59], v[4:5], v[58:59]
	v_pk_mul_f32 v[60:61], v[6:7], v[60:61]
	global_store_dwordx4 v[76:77], v[58:61], off offset:512
	s_nop 1
	v_pk_mul_f32 v[58:59], v[176:177], v[78:79] op_sel_hi:[1,0]
	v_pk_mul_f32 v[60:61], v[84:85], v[78:79] op_sel_hi:[1,0]
	v_pk_mul_f32 v[58:59], v[0:1], v[58:59]
	v_pk_mul_f32 v[60:61], v[2:3], v[60:61]
	global_store_dwordx4 v[76:77], v[58:61], off offset:528
	s_nop 1
	v_mul_f32_e32 v58, 0x45800000, v62
	v_cndmask_b32_e32 v58, v62, v58, vcc
	v_lshlrev_b64 v[60:61], 13, v[72:73]
	v_lshl_add_u64 v[60:61], s[58:59], 0, v[60:61]
	v_pk_mul_f32 v[44:45], v[44:45], v[58:59] op_sel_hi:[1,0]
	v_pk_mul_f32 v[46:47], v[46:47], v[58:59] op_sel_hi:[1,0]
	v_lshl_add_u64 v[60:61], v[60:61], 0, v[164:165]
	v_pk_mul_f32 v[46:47], v[14:15], v[46:47]
	v_pk_mul_f32 v[44:45], v[12:13], v[44:45]
	global_store_dwordx4 v[60:61], v[44:47], off
	v_pk_mul_f32 v[42:43], v[42:43], v[58:59] op_sel_hi:[1,0]
	s_nop 0
	v_pk_mul_f32 v[46:47], v[66:67], v[58:59] op_sel_hi:[1,0]
	v_pk_mul_f32 v[44:45], v[10:11], v[42:43]
	v_pk_mul_f32 v[42:43], v[8:9], v[46:47]
	global_store_dwordx4 v[60:61], v[42:45], off offset:16
	s_nop 1
	v_pk_mul_f32 v[42:43], v[70:71], v[58:59] op_sel_hi:[1,0]
	v_pk_mul_f32 v[44:45], v[64:65], v[58:59] op_sel_hi:[1,0]
	v_pk_mul_f32 v[42:43], v[4:5], v[42:43]
	v_pk_mul_f32 v[44:45], v[6:7], v[44:45]
	global_store_dwordx4 v[60:61], v[42:45], off offset:512
	s_nop 1
	v_pk_mul_f32 v[42:43], v[178:179], v[58:59] op_sel_hi:[1,0]
	v_pk_mul_f32 v[44:45], v[68:69], v[58:59] op_sel_hi:[1,0]
	v_pk_mul_f32 v[42:43], v[0:1], v[42:43]
	v_pk_mul_f32 v[44:45], v[2:3], v[44:45]
	global_store_dwordx4 v[60:61], v[42:45], off offset:528
	s_waitcnt vmcnt(24)
	s_nop 0
	v_pk_fma_f32 v[42:43], v[180:181], s[22:23], v[170:171] op_sel_hi:[1,0,0]
	s_nop 0
	v_mul_f32_e32 v44, 0x4b800000, v43
	v_cmp_gt_f32_e32 vcc, s48, v43
	s_nop 1
	v_cndmask_b32_e32 v43, v43, v44, vcc
	v_rsq_f32_e32 v43, v43
	v_lshlrev_b64 v[44:45], 13, v[56:57]
	v_lshl_add_u64 v[44:45], s[58:59], 0, v[44:45]
	v_lshl_add_u64 v[44:45], v[44:45], 0, v[164:165]
	v_mul_f32_e32 v46, 0x45800000, v43
	v_cndmask_b32_e32 v46, v43, v46, vcc
	v_pk_mul_f32 v[20:21], v[20:21], v[46:47] op_sel_hi:[1,0]
	v_pk_mul_f32 v[22:23], v[22:23], v[46:47] op_sel_hi:[1,0]
	v_pk_mul_f32 v[20:21], v[4:5], v[20:21]
	v_pk_mul_f32 v[22:23], v[6:7], v[22:23]
	global_store_dwordx4 v[44:45], v[20:23], off offset:512
	v_cmp_gt_f32_e32 vcc, s48, v42
	v_pk_mul_f32 v[16:17], v[16:17], v[46:47] op_sel_hi:[1,0]
	v_mul_f32_e32 v20, 0x4b800000, v42
	v_cndmask_b32_e32 v20, v42, v20, vcc
	v_rsq_f32_e32 v20, v20
	v_pk_mul_f32 v[18:19], v[18:19], v[46:47] op_sel_hi:[1,0]
	v_pk_mul_f32 v[16:17], v[0:1], v[16:17]
	v_pk_mul_f32 v[18:19], v[2:3], v[18:19]
	global_store_dwordx4 v[44:45], v[16:19], off offset:528
	v_pk_mul_f32 v[28:29], v[28:29], v[46:47] op_sel_hi:[1,0]
	v_pk_mul_f32 v[30:31], v[30:31], v[46:47] op_sel_hi:[1,0]
	v_mul_f32_e32 v16, 0x45800000, v20
	v_cndmask_b32_e32 v16, v20, v16, vcc
	v_lshlrev_b64 v[18:19], 13, v[40:41]
	v_lshl_add_u64 v[18:19], s[58:59], 0, v[18:19]
	v_pk_mul_f32 v[20:21], v[36:37], v[16:17] op_sel_hi:[1,0]
	v_pk_mul_f32 v[22:23], v[32:33], v[16:17] op_sel_hi:[1,0]
	v_pk_mul_f32 v[30:31], v[14:15], v[30:31]
	v_pk_mul_f32 v[28:29], v[12:13], v[28:29]
	v_lshl_add_u64 v[18:19], v[18:19], 0, v[164:165]
	v_pk_mul_f32 v[14:15], v[14:15], v[22:23]
	v_pk_mul_f32 v[12:13], v[12:13], v[20:21]
	global_store_dwordx4 v[44:45], v[28:31], off
	v_pk_mul_f32 v[24:25], v[24:25], v[46:47] op_sel_hi:[1,0]
	v_pk_mul_f32 v[26:27], v[26:27], v[46:47] op_sel_hi:[1,0]
	global_store_dwordx4 v[18:19], v[12:15], off
	v_pk_mul_f32 v[26:27], v[10:11], v[26:27]
	v_pk_mul_f32 v[24:25], v[8:9], v[24:25]
	v_pk_mul_f32 v[12:13], v[48:49], v[16:17] op_sel_hi:[1,0]
	v_pk_mul_f32 v[14:15], v[34:35], v[16:17] op_sel_hi:[1,0]
	v_pk_mul_f32 v[8:9], v[8:9], v[12:13]
	v_pk_mul_f32 v[10:11], v[10:11], v[14:15]
	global_store_dwordx4 v[44:45], v[24:27], off offset:16
	global_store_dwordx4 v[18:19], v[8:11], off offset:16
	s_and_b64 vcc, exec, s[8:9]
	s_nop 0
	v_pk_mul_f32 v[8:9], v[52:53], v[16:17] op_sel_hi:[1,0]
	v_pk_mul_f32 v[10:11], v[38:39], v[16:17] op_sel_hi:[1,0]
	v_pk_mul_f32 v[4:5], v[4:5], v[8:9]
	v_pk_mul_f32 v[6:7], v[6:7], v[10:11]
	global_store_dwordx4 v[18:19], v[4:7], off offset:512
	s_nop 1
	v_pk_mul_f32 v[4:5], v[54:55], v[16:17] op_sel_hi:[1,0]
	v_pk_mul_f32 v[6:7], v[50:51], v[16:17] op_sel_hi:[1,0]
	v_pk_mul_f32 v[0:1], v[0:1], v[4:5]
	v_pk_mul_f32 v[2:3], v[2:3], v[6:7]
	global_store_dwordx4 v[18:19], v[0:3], off offset:528
	s_cbranch_vccnz .LBB0_1118
	s_andn2_b64 vcc, exec, s[14:15]
	s_cbranch_vccnz .LBB0_1117
	s_barrier
	s_branch .LBB0_1117
